# x->bf16/row-rms conversion of rows>=12288 moved into the projection GEMM phase (XCD-local unit order + per-round counters)
# speedup vs baseline: 1.1393x; 1.0177x over previous
.LBB0_24:
	s_or_b64 exec, exec, s[44:45]
	s_add_u32 s30, s30, s80
	s_addc_u32 s31, s31, s81
	s_add_u32 s8, s8, s28
	s_addc_u32 s9, s9, s29
	s_cmp_gt_i32 s30, 0x2fff
	s_cbranch_scc1 .LBB0_29

.LBB0_29:
	s_mov_b32 s32, 0
	s_cmpk_lg_i32 s54, 0x100
	s_cbranch_scc1 .Lxt_skip
	s_cmp_lg_u32 s74, 0
	s_cbranch_scc1 .Lxt_skip
	s_lshl_b32 s56, 1, s79
	s_lshr_b32 s57, s75, 5
	s_lshl_b32 s57, s57, 2
	s_add_u32 s58, s42, 0x60d3c00
	s_addc_u32 s59, s43, 0
	v_mov_b32_e32 v40, s57
	v_mov_b32_e32 v41, s56
	s_mov_b64 s[60:61], exec
	s_mov_b64 exec, 1
	global_atomic_or v40, v41, s[58:59] sc1
	s_mov_b64 exec, s[60:61]

.LBB0_109:
	s_cmpk_lg_i32 s54, 0x100
	s_cbranch_scc1 .Lp01_fb
	s_add_u32 s66, s42, 0x60d3c00
	s_addc_u32 s67, s43, 0
	v_mov_b32_e32 v20, 0
	global_load_dwordx4 v[24:27], v20, s[66:67] sc1
	global_load_dwordx4 v[28:31], v20, s[66:67] offset:16 sc1
	s_waitcnt vmcnt(0)
	v_readfirstlane_b32 s66, v24
	s_bcnt1_i32_b32 s66, s66
	s_cmp_lg_u32 s66, 1
	s_cbranch_scc1 .Lp01_fb
	v_readfirstlane_b32 s66, v25
	s_bcnt1_i32_b32 s66, s66
	s_cmp_lg_u32 s66, 1
	s_cbranch_scc1 .Lp01_fb
	v_readfirstlane_b32 s66, v26
	s_bcnt1_i32_b32 s66, s66
	s_cmp_lg_u32 s66, 1
	s_cbranch_scc1 .Lp01_fb
	v_readfirstlane_b32 s66, v27
	s_bcnt1_i32_b32 s66, s66
	s_cmp_lg_u32 s66, 1
	s_cbranch_scc1 .Lp01_fb
	v_readfirstlane_b32 s66, v28
	s_bcnt1_i32_b32 s66, s66
	s_cmp_lg_u32 s66, 1
	s_cbranch_scc1 .Lp01_fb
	v_readfirstlane_b32 s66, v29
	s_bcnt1_i32_b32 s66, s66
	s_cmp_lg_u32 s66, 1
	s_cbranch_scc1 .Lp01_fb
	v_readfirstlane_b32 s66, v30
	s_bcnt1_i32_b32 s66, s66
	s_cmp_lg_u32 s66, 1
	s_cbranch_scc1 .Lp01_fb
	v_readfirstlane_b32 s66, v31
	s_bcnt1_i32_b32 s66, s66
	s_cmp_lg_u32 s66, 1
	s_cbranch_scc1 .Lp01_fb
	s_mov_b32 s32, 1
	s_branch .Lp01_dec_done
.Lp01_fb:
	v_mov_b32_e32 v86, 0x358637bd
	v_mov_b32_e32 v87, 0
	v_lshlrev_b32_e32 v88, 4, v190
	v_xor_b32_e32 v80, 1, v190
	v_lshlrev_b32_e32 v80, 2, v80
	v_xor_b32_e32 v81, 2, v190
	v_lshlrev_b32_e32 v81, 2, v81
	v_xor_b32_e32 v82, 4, v190
	v_lshlrev_b32_e32 v82, 2, v82
	v_xor_b32_e32 v83, 8, v190
	v_lshlrev_b32_e32 v83, 2, v83
	v_xor_b32_e32 v84, 16, v190
	v_lshlrev_b32_e32 v84, 2, v84
	v_xor_b32_e32 v85, 32, v190
	v_lshlrev_b32_e32 v85, 2, v85
	s_add_i32 s66, s10, 0x3000
.Lp01_fb_loop:
	s_cmp_gt_u32 s66, 0xbfff
	s_cbranch_scc1 .Lp01_fb_done
	s_cmp_lt_u32 s66, 0x8000
	s_cselect_b32 s68, s12, s14
	s_cselect_b32 s69, s13, s15
	s_cselect_b32 s67, 0, 0x8000
	s_sub_u32 s67, s66, s67
	s_lshl_b32 s67, s67, 12
	s_add_u32 s68, s68, s67
	s_addc_u32 s69, s69, 0
	global_load_dwordx4 v[18:21], v88, s[68:69] offset:0 nt
	global_load_dwordx4 v[22:25], v88, s[68:69] offset:1024 nt
	global_load_dwordx4 v[26:29], v88, s[68:69] offset:2048 nt
	global_load_dwordx4 v[30:33], v88, s[68:69] offset:3072 nt
	s_lshl_b32 s67, s66, 11
	s_add_u32 s86, s42, s67
	s_addc_u32 s87, s43, 0
	s_waitcnt vmcnt(0)
	v_mul_f32_e32 v66, v19, v19
	v_mul_f32_e32 v67, v23, v23
	v_mul_f32_e32 v68, v27, v27
	v_fmac_f32_e32 v66, v18, v18
	v_fmac_f32_e32 v67, v22, v22
	v_mul_f32_e32 v69, v31, v31
	v_fmac_f32_e32 v68, v26, v26
	v_fmac_f32_e32 v66, v20, v20
	v_fmac_f32_e32 v67, v24, v24
	v_fmac_f32_e32 v69, v30, v30
	v_fmac_f32_e32 v68, v28, v28
	v_fmac_f32_e32 v66, v21, v21
	v_fmac_f32_e32 v67, v25, v25
	v_fmac_f32_e32 v69, v32, v32
	v_fmac_f32_e32 v68, v29, v29
	v_add_f32_e32 v66, v66, v67
	v_fmac_f32_e32 v69, v33, v33
	v_add_f32_e32 v66, v66, v68
	v_add_f32_e32 v72, v66, v69
	v_cvt_pk_bf16_f32 v18, v18, v19
	v_cvt_pk_bf16_f32 v19, v20, v21
	v_cvt_pk_bf16_f32 v20, v22, v23
	v_cvt_pk_bf16_f32 v21, v24, v25
	v_cvt_pk_bf16_f32 v22, v26, v27
	v_cvt_pk_bf16_f32 v23, v28, v29
	v_cvt_pk_bf16_f32 v24, v30, v31
	v_cvt_pk_bf16_f32 v25, v32, v33
	global_store_dwordx2 v188, v[18:19], s[86:87] offset:0
	global_store_dwordx2 v188, v[20:21], s[86:87] offset:512
	global_store_dwordx2 v188, v[22:23], s[86:87] offset:1024
	global_store_dwordx2 v188, v[24:25], s[86:87] offset:1536
	ds_bpermute_b32 v76, v80, v72
	s_waitcnt lgkmcnt(0)
	v_add_f32_e32 v72, v72, v76
	ds_bpermute_b32 v76, v81, v72
	s_waitcnt lgkmcnt(0)
	v_add_f32_e32 v72, v72, v76
	ds_bpermute_b32 v76, v82, v72
	s_waitcnt lgkmcnt(0)
	v_add_f32_e32 v72, v72, v76
	ds_bpermute_b32 v76, v83, v72
	s_waitcnt lgkmcnt(0)
	v_add_f32_e32 v72, v72, v76
	ds_bpermute_b32 v76, v84, v72
	s_waitcnt lgkmcnt(0)
	v_add_f32_e32 v72, v72, v76
	ds_bpermute_b32 v76, v85, v72
	s_waitcnt lgkmcnt(0)
	v_add_f32_e32 v72, v72, v76
	v_fmamk_f32 v72, v72, 0x3a800000, v86
	v_rsq_f32_e32 v72, v72
	s_nop 0
	s_mov_b64 s[94:95], exec
	s_mov_b64 exec, 1
	s_lshl_b32 s67, s66, 2
	s_add_u32 s92, s42, s67
	s_addc_u32 s93, s43, 0
	s_add_u32 s92, s92, 0x6000000
	s_addc_u32 s93, s93, 0
	global_store_dword v87, v72, s[92:93]
	s_mov_b64 exec, s[94:95]
	s_add_i32 s66, s66, s80
	s_branch .Lp01_fb_loop
.Lp01_fb_done:
.Lp01_dec_done:
	s_waitcnt vmcnt(0)
	v_writelane_b32 v254, s80, 11
	s_barrier
	s_nop 0
	v_writelane_b32 v254, s81, 12
	s_mov_b64 s[0:1], exec
	v_readlane_b32 s2, v254, 1
	v_readlane_b32 s3, v254, 2
	s_and_b64 s[2:3], s[0:1], s[2:3]
	s_mov_b64 exec, s[2:3]
	s_cbranch_execz .LBB0_161
	s_add_i32 s2, 0, 0x20000
	v_mov_b32_e32 v0, s2
	s_waitcnt vmcnt(0) expcnt(0) lgkmcnt(0)
	ds_read_b32 v2, v0
	s_add_i32 s2, 0, 0x20004
	v_mov_b32_e32 v0, s2
	ds_read_b32 v0, v0
	s_waitcnt lgkmcnt(1)
	v_cmp_ne_u32_e32 vcc, 0, v2
	s_cbranch_vccnz .LBB0_125
	v_readlane_b32 s2, v254, 0
	s_mul_i32 s33, s55, s2
	s_add_u32 s2, s42, 0x60d0200
	s_addc_u32 s3, s43, 0
	s_add_u32 s4, s42, 0x60d0400
	s_addc_u32 s5, s43, 0
	s_add_u32 s8, s42, 0x60d0500
	s_addc_u32 s9, s43, 0
	s_add_u32 s16, s42, 0x60d0600
	s_addc_u32 s17, s43, 0
	s_add_u32 s18, s42, 0x60d0700
	s_addc_u32 s19, s43, 0
	s_add_u32 s24, s42, 0x60d0800
	s_addc_u32 s25, s43, 0
	s_add_u32 s28, s42, 0x60d0900
	s_addc_u32 s29, s43, 0
	s_add_u32 s30, s42, 0x60d0a00
	s_addc_u32 s31, s43, 0
	s_add_u32 s34, s42, 0x60d0b00
	s_addc_u32 s35, s43, 0
	s_add_u32 s36, s42, 0x60d0c00
	s_addc_u32 s37, s43, 0
	s_add_u32 s44, s42, 0x60d0d00
	s_addc_u32 s45, s43, 0
	s_add_u32 s46, s42, 0x60d0e00
	s_addc_u32 s47, s43, 0
	s_add_u32 s50, s42, 0x60d0f00
	s_addc_u32 s51, s43, 0
	s_add_u32 s52, s42, 0x60d1000
	s_addc_u32 s53, s43, 0
	s_mul_i32 s33, s33, s54
	s_add_u32 s54, s42, 0x60d1100
	s_addc_u32 s55, s43, 0
	s_add_u32 s56, s42, 0x60d1200
	s_addc_u32 s57, s43, 0
	s_add_u32 s58, s42, 0x60d1300
	s_addc_u32 s59, s43, 0
	s_mov_b32 s66, 1
	v_mov_b32_e32 v16, 0
	s_branch .LBB0_113

.LBB0_161:
	v_writelane_b32 v254, s79, 13
	v_writelane_b32 v254, s82, 14
	s_nop 1
	v_writelane_b32 v254, s83, 15
	s_or_b64 exec, exec, s[0:1]
	s_add_u32 s0, s42, 0x7000000
	s_addc_u32 s1, s43, 0
	v_writelane_b32 v254, s0, 16
	v_and_b32_e32 v189, 31, v191
	v_lshrrev_b32_e32 v197, 5, v190
	v_writelane_b32 v254, s1, 17
	s_add_u32 s0, s42, 0xa000000
	s_addc_u32 s1, s43, 0
	v_writelane_b32 v254, s0, 18
	s_waitcnt lgkmcnt(0)
	v_bfe_u32 v0, v191, 2, 2
	v_lshrrev_b32_e32 v193, 2, v190
	v_writelane_b32 v254, s1, 19
	s_add_u32 s0, s42, 0xac00000
	v_writelane_b32 v254, s0, 20
	s_addc_u32 s0, s43, 0
	v_writelane_b32 v254, s0, 21
	s_add_u32 s0, s42, 0xb800000
	s_addc_u32 s1, s43, 0
	v_writelane_b32 v254, s0, 22
	v_lshrrev_b32_e32 v216, 4, v191
	v_lshrrev_b32_e32 v215, 2, v191
	v_writelane_b32 v254, s1, 23
	s_add_u32 s0, s42, 0xe800000
	s_addc_u32 s1, s43, 0
	v_writelane_b32 v254, s0, 24
	v_bitop3_b32 v214, v197, v0, 2 bitop3:0x36
	v_lshlrev_b32_e32 v192, 2, v197
	v_writelane_b32 v254, s1, 25
	s_lshr_b32 s0, s84, 8
	v_writelane_b32 v254, s0, 26
	s_bfe_u32 s0, s84, 0x20006
	v_writelane_b32 v254, s84, 27
	s_cmpk_gt_i32 s75, 0x83f
	v_cmp_gt_u32_e64 s[2:3], 32, v190
	v_lshlrev_b32_e32 v220, 3, v191
	v_lshrrev_b32_e32 v219, 1, v191
	v_or_b32_e32 v213, 32, v189
	v_lshlrev_b32_e32 v212, 4, v191
	s_barrier
	v_writelane_b32 v254, s0, 28
	s_cbranch_scc1 .LBB0_181
	v_readlane_b32 s0, v254, 28
	s_lshl_b32 s5, s0, 6
	s_lshl_b32 s0, s74, 1
	v_readlane_b32 s1, v254, 27
	s_cmpk_lt_u32 s1, 0x100
	s_cselect_b64 s[8:9], -1, 0
	v_writelane_b32 v254, s8, 29
	v_bitop3_b32 v1, v197, v215, 3 bitop3:0x78
	v_lshlrev_b32_e32 v152, 4, v1
	v_writelane_b32 v254, s9, 30
	v_mov_b32_e32 v133, 0
	v_readlane_b32 s4, v254, 26
	s_lshl_b32 s1, s4, 5
	v_or_b32_e32 v1, s1, v197
	v_bitop3_b32 v3, v189, s1, v197 bitop3:0x1e
	v_lshlrev_b32_e32 v154, 3, v3
	v_bitop3_b32 v3, v189, v1, 32 bitop3:0x36
	v_lshlrev_b32_e32 v155, 3, v3
	v_or_b32_e32 v3, 2, v1
	v_bitop3_b32 v3, v189, v3, 32 bitop3:0x36
	v_lshlrev_b32_e32 v157, 3, v3
	v_or_b32_e32 v3, 4, v1
	v_bitop3_b32 v3, v189, v3, 32 bitop3:0x36
	v_lshlrev_b32_e32 v159, 3, v3
	v_or_b32_e32 v3, 6, v1
	v_bitop3_b32 v3, v189, v3, 32 bitop3:0x36
	v_lshlrev_b32_e32 v161, 3, v3
	v_or_b32_e32 v3, 8, v1
	v_bitop3_b32 v3, v189, v3, 32 bitop3:0x36
	v_lshlrev_b32_e32 v163, 3, v3
	v_or_b32_e32 v3, 10, v1
	v_bitop3_b32 v3, v189, v3, 32 bitop3:0x36
	v_lshlrev_b32_e32 v165, 3, v3
	v_or_b32_e32 v3, 12, v1
	v_bitop3_b32 v3, v189, v3, 32 bitop3:0x36
	v_lshlrev_b32_e32 v167, 3, v3
	v_or_b32_e32 v3, 14, v1
	v_bitop3_b32 v3, v189, v3, 32 bitop3:0x36
	v_bitop3_b32 v4, v189, v1, 2 bitop3:0x1e
	v_lshlrev_b32_e32 v169, 3, v3
	v_or_b32_e32 v3, 16, v1
	v_lshlrev_b32_e32 v156, 3, v4
	v_bitop3_b32 v4, v189, v1, 4 bitop3:0x1e
	v_bitop3_b32 v3, v189, v3, 32 bitop3:0x36
	v_lshlrev_b32_e32 v158, 3, v4
	v_bitop3_b32 v4, v189, v1, 6 bitop3:0x1e
	v_lshlrev_b32_e32 v171, 3, v3
	v_or_b32_e32 v3, 18, v1
	v_lshlrev_b32_e32 v160, 3, v4
	v_bitop3_b32 v4, v189, v1, 8 bitop3:0x1e
	v_bitop3_b32 v3, v189, v3, 32 bitop3:0x36
	v_lshlrev_b32_e32 v162, 3, v4
	v_bitop3_b32 v4, v189, v1, 10 bitop3:0x1e
	v_lshlrev_b32_e32 v173, 3, v3
	v_or_b32_e32 v3, 20, v1
	v_lshlrev_b32_e32 v164, 3, v4
	v_bitop3_b32 v4, v189, v1, 12 bitop3:0x1e
	v_bitop3_b32 v3, v189, v3, 32 bitop3:0x36
	v_lshlrev_b32_e32 v166, 3, v4
	v_bitop3_b32 v4, v189, v1, 14 bitop3:0x1e
	v_lshlrev_b32_e32 v175, 3, v3
	v_or_b32_e32 v3, 22, v1
	v_lshlrev_b32_e32 v168, 3, v4
	v_bitop3_b32 v4, v189, v1, 16 bitop3:0x1e
	v_bitop3_b32 v3, v189, v3, 32 bitop3:0x36
	v_lshlrev_b32_e32 v170, 3, v4
	v_bitop3_b32 v4, v189, v1, 18 bitop3:0x1e
	v_lshlrev_b32_e32 v177, 3, v3
	v_or_b32_e32 v3, 24, v1
	v_lshlrev_b32_e32 v172, 3, v4
	v_bitop3_b32 v4, v189, v1, 20 bitop3:0x1e
	v_bitop3_b32 v3, v189, v3, 32 bitop3:0x36
	v_lshlrev_b32_e32 v174, 3, v4
	v_bitop3_b32 v4, v189, v1, 22 bitop3:0x1e
	v_lshlrev_b32_e32 v179, 3, v3
	v_or_b32_e32 v3, 26, v1
	v_lshlrev_b32_e32 v176, 3, v4
	v_bitop3_b32 v4, v189, v1, 24 bitop3:0x1e
	v_bitop3_b32 v3, v189, v3, 32 bitop3:0x36
	v_lshlrev_b32_e32 v2, 1, v191
	v_lshlrev_b32_e32 v178, 3, v4
	v_bitop3_b32 v4, v189, v1, 26 bitop3:0x1e
	v_lshlrev_b32_e32 v181, 3, v3
	v_or_b32_e32 v3, 28, v1
	v_or_b32_e32 v134, s0, v197
	v_and_b32_e32 v2, 8, v2
	v_lshlrev_b32_e32 v180, 3, v4
	v_bitop3_b32 v4, v189, v1, 28 bitop3:0x1e
	v_bitop3_b32 v3, v189, v3, 32 bitop3:0x36
	v_add_u32_e32 v132, 16, v134
	v_mov_b32_e32 v135, v133
	v_and_or_b32 v153, v219, 4, v2
	v_lshlrev_b32_e32 v2, 1, v197
	v_lshlrev_b32_e32 v182, 3, v4
	v_lshlrev_b32_e32 v183, 3, v3
	v_or_b32_e32 v3, 30, v1
	v_bitop3_b32 v1, v189, v1, 30 bitop3:0x1e
	v_lshlrev_b64 v[136:137], 10, v[132:133]
	v_and_b32_e32 v4, 0x1f0, v212
	v_lshlrev_b64 v[138:139], 10, v[134:135]
	v_lshlrev_b32_e32 v184, 3, v1
	v_bitop3_b32 v1, v189, v3, 32 bitop3:0x36
	v_or_b32_e32 v3, 1, v2
	v_or_b32_e32 v136, v136, v4
	v_or_b32_e32 v138, v138, v4
	v_or_b32_e32 v4, 4, v2
	v_lshlrev_b32_e32 v185, 3, v1
	v_cvt_f32_ubyte0_e32 v1, v2
	v_cvt_f32_ubyte0_e32 v3, v3
	v_cvt_f32_ubyte0_e32 v4, v4
	v_mul_f32_e32 v1, 0xbf549a78, v1
	v_mul_f32_e32 v3, 0xbf549a78, v3
	v_mul_f32_e32 v4, 0xbf549a78, v4
	v_exp_f32_e32 v1, v1
	v_exp_f32_e32 v3, v3
	v_exp_f32_e32 v4, v4
	v_or_b32_e32 v5, 5, v2
	v_mul_f32_e32 v186, 0.15915494, v1
	v_mul_f32_e32 v187, 0.15915494, v3
	v_mul_f32_e32 v194, 0.15915494, v4
	v_or_b32_e32 v1, 8, v2
	v_or_b32_e32 v3, 9, v2
	v_or_b32_e32 v4, 12, v2
	v_or_b32_e32 v2, 13, v2
	v_cvt_f32_ubyte0_e32 v5, v5
	v_cvt_f32_ubyte0_e32 v1, v1
	v_cvt_f32_ubyte0_e32 v3, v3
	v_cvt_f32_ubyte0_e32 v4, v4
	v_cvt_f32_ubyte0_e32 v2, v2
	v_mul_f32_e32 v5, 0xbf549a78, v5
	v_mul_f32_e32 v1, 0xbf549a78, v1
	v_mul_f32_e32 v3, 0xbf549a78, v3
	v_mul_f32_e32 v4, 0xbf549a78, v4
	v_mul_f32_e32 v2, 0xbf549a78, v2
	v_xor_b32_e32 v0, v216, v191
	v_exp_f32_e32 v5, v5
	v_exp_f32_e32 v1, v1
	v_exp_f32_e32 v3, v3
	v_exp_f32_e32 v4, v4
	v_exp_f32_e32 v2, v2
	v_lshlrev_b32_e32 v0, 3, v0
	s_add_i32 s0, s0, 16
	s_lshl_b32 s8, s4, 1
	s_lshr_b32 s64, s0, 1
	s_lshl_b32 s0, s74, 10
	v_and_b32_e32 v0, 24, v0
	v_writelane_b32 v254, s8, 31
	s_add_i32 s0, s0, 0
	v_lshlrev_b32_e32 v140, 1, v0
	v_or_b32_e32 v203, s5, v189
	v_and_b32_e32 v0, 0xf8, v220
	s_mov_b32 s51, 0
	v_mul_f32_e32 v195, 0.15915494, v5
	v_mul_f32_e32 v196, 0.15915494, v1
	v_mul_f32_e32 v198, 0.15915494, v3
	v_mul_f32_e32 v199, 0.15915494, v4
	v_mul_f32_e32 v200, 0.15915494, v2
	s_mov_b64 s[56:57], 0x80
	v_lshlrev_b32_e32 v201, 4, v214
	v_lshl_or_b32 v202, s4, 7, v192
	v_writelane_b32 v254, s5, 32
	v_lshl_add_u32 v204, v203, 9, 0
	v_cvt_f32_ubyte0_e32 v205, v189
	v_lshl_add_u32 v206, v197, 9, s0
	v_mov_b64_e32 v[142:143], v[132:133]
	v_lshlrev_b32_e32 v144, 1, v0
	v_cvt_f32_ubyte0_e32 v207, v213
	v_mov_b32_e32 v208, 0x358637bd
	v_mbcnt_hi_u32_b32 v209, -1, v218
	s_mov_b32 s65, 0x800000
	s_mov_b32 s33, s75
	s_mov_b64 s[70:71], 0x40540
	s_mov_b64 s[72:73], 0x580
	s_mov_b64 s[60:61], 0x40580
	s_mov_b64 s[62:63], 0x5c0
	s_mov_b64 s[66:67], 0x405c0
	s_mov_b64 s[80:81], 0x600
	s_mov_b64 s[82:83], 0x40600
	s_mov_b64 s[84:85], 0x640
	s_mov_b64 s[86:87], 0x40640
	s_mov_b64 s[88:89], 0x680
	s_mov_b64 s[90:91], 0x40680
	s_mov_b64 s[92:93], 0x6c0
	s_mov_b64 s[94:95], 0x406c0
	s_mov_b64 s[96:97], 0x700
	s_mov_b64 s[98:99], 0x40700
	s_mov_b64 s[30:31], 0x740
	s_mov_b64 s[16:17], 0x40740
	s_mov_b64 s[0:1], 0x780
	s_mov_b64 s[34:35], 0x40780
	s_mov_b64 s[4:5], 0x7c0
	s_mov_b64 s[8:9], 0x407c0
	s_mov_b64 s[36:37], 0x8000
	s_cmp_eq_u32 s32, 0
	s_cbranch_scc1 .LBB0_164
	s_mov_b32 s60, 0
	s_lshr_b32 s61, s75, 5
	s_and_b32 s62, s75, 31
	s_and_b32 s63, s75, 1
	s_branch .Lp01_next
.LBB0_163:
	v_readlane_b32 s18, v254, 9
	v_readlane_b32 s19, v254, 10
	s_cmp_eq_u32 s32, 0
	s_cbranch_scc0 .Lp01_next
	s_add_i32 s33, s33, s18
	s_cmpk_gt_i32 s33, 0x83f
	s_cbranch_scc1 .LBB0_181
	s_branch .LBB0_164
.Lp01_next:
	s_lshl_b32 s66, s60, 5
	s_add_i32 s66, s66, s62
	s_cmpk_gt_u32 s66, 0x107
	s_cbranch_scc1 .LBB0_181
	s_sub_i32 s96, s60, s63
	s_cmp_gt_u32 s96, 5
	s_cbranch_scc1 .Lp01_noprod
	s_mul_i32 s66, s96, 3
	s_add_i32 s66, s66, 6
	s_lshl_b32 s66, s66, 3
	s_add_i32 s66, s66, s61
	s_lshl_b32 s66, s66, 8
	s_lshl_b32 s67, s62, 3
	s_add_i32 s66, s66, s67
	s_add_i32 s66, s66, s74
	s_add_i32 s97, s66, 0x800
	s_add_i32 s98, s66, 0x1000
	v_mov_b32_e32 v86, 0x358637bd
	v_mov_b32_e32 v87, 0
	v_lshlrev_b32_e32 v88, 4, v190
	v_xor_b32_e32 v80, 1, v190
	v_lshlrev_b32_e32 v80, 2, v80
	v_xor_b32_e32 v81, 2, v190
	v_lshlrev_b32_e32 v81, 2, v81
	v_xor_b32_e32 v82, 4, v190
	v_lshlrev_b32_e32 v82, 2, v82
	v_xor_b32_e32 v83, 8, v190
	v_lshlrev_b32_e32 v83, 2, v83
	v_xor_b32_e32 v84, 16, v190
	v_lshlrev_b32_e32 v84, 2, v84
	v_xor_b32_e32 v85, 32, v190
	v_lshlrev_b32_e32 v85, 2, v85
	s_cmp_lt_u32 s66, 0x8000
	s_cselect_b32 s68, s12, s14
	s_cselect_b32 s69, s13, s15
	s_cselect_b32 s67, 0, 0x8000
	s_sub_u32 s67, s66, s67
	s_lshl_b32 s67, s67, 12
	s_add_u32 s68, s68, s67
	s_addc_u32 s69, s69, 0
	global_load_dwordx4 v[18:21], v88, s[68:69] offset:0 nt
	global_load_dwordx4 v[22:25], v88, s[68:69] offset:1024 nt
	global_load_dwordx4 v[26:29], v88, s[68:69] offset:2048 nt
	global_load_dwordx4 v[30:33], v88, s[68:69] offset:3072 nt
	s_cmp_lt_u32 s97, 0x8000
	s_cselect_b32 s70, s12, s14
	s_cselect_b32 s71, s13, s15
	s_cselect_b32 s67, 0, 0x8000
	s_sub_u32 s67, s97, s67
	s_lshl_b32 s67, s67, 12
	s_add_u32 s70, s70, s67
	s_addc_u32 s71, s71, 0
	global_load_dwordx4 v[34:37], v88, s[70:71] offset:0 nt
	global_load_dwordx4 v[38:41], v88, s[70:71] offset:1024 nt
	global_load_dwordx4 v[42:45], v88, s[70:71] offset:2048 nt
	global_load_dwordx4 v[46:49], v88, s[70:71] offset:3072 nt
	s_cmp_lt_u32 s98, 0x8000
	s_cselect_b32 s72, s12, s14
	s_cselect_b32 s73, s13, s15
	s_cselect_b32 s67, 0, 0x8000
	s_sub_u32 s67, s98, s67
	s_lshl_b32 s67, s67, 12
	s_add_u32 s72, s72, s67
	s_addc_u32 s73, s73, 0
	global_load_dwordx4 v[50:53], v88, s[72:73] offset:0 nt
	global_load_dwordx4 v[54:57], v88, s[72:73] offset:1024 nt
	global_load_dwordx4 v[58:61], v88, s[72:73] offset:2048 nt
	global_load_dwordx4 v[62:65], v88, s[72:73] offset:3072 nt
	s_lshl_b32 s67, s66, 11
	s_add_u32 s86, s42, s67
	s_addc_u32 s87, s43, 0
	s_waitcnt vmcnt(8)
	v_mul_f32_e32 v66, v19, v19
	v_mul_f32_e32 v67, v23, v23
	v_mul_f32_e32 v68, v27, v27
	v_fmac_f32_e32 v66, v18, v18
	v_fmac_f32_e32 v67, v22, v22
	v_mul_f32_e32 v69, v31, v31
	v_fmac_f32_e32 v68, v26, v26
	v_fmac_f32_e32 v66, v20, v20
	v_fmac_f32_e32 v67, v24, v24
	v_fmac_f32_e32 v69, v30, v30
	v_fmac_f32_e32 v68, v28, v28
	v_fmac_f32_e32 v66, v21, v21
	v_fmac_f32_e32 v67, v25, v25
	v_fmac_f32_e32 v69, v32, v32
	v_fmac_f32_e32 v68, v29, v29
	v_add_f32_e32 v66, v66, v67
	v_fmac_f32_e32 v69, v33, v33
	v_add_f32_e32 v66, v66, v68
	v_add_f32_e32 v72, v66, v69
	v_cvt_pk_bf16_f32 v18, v18, v19
	v_cvt_pk_bf16_f32 v19, v20, v21
	v_cvt_pk_bf16_f32 v20, v22, v23
	v_cvt_pk_bf16_f32 v21, v24, v25
	v_cvt_pk_bf16_f32 v22, v26, v27
	v_cvt_pk_bf16_f32 v23, v28, v29
	v_cvt_pk_bf16_f32 v24, v30, v31
	v_cvt_pk_bf16_f32 v25, v32, v33
	global_store_dwordx2 v188, v[18:19], s[86:87] offset:0
	global_store_dwordx2 v188, v[20:21], s[86:87] offset:512
	global_store_dwordx2 v188, v[22:23], s[86:87] offset:1024
	global_store_dwordx2 v188, v[24:25], s[86:87] offset:1536
	s_lshl_b32 s67, s97, 11
	s_add_u32 s88, s42, s67
	s_addc_u32 s89, s43, 0
	s_waitcnt vmcnt(8)
	v_mul_f32_e32 v66, v35, v35
	v_mul_f32_e32 v67, v39, v39
	v_mul_f32_e32 v68, v43, v43
	v_fmac_f32_e32 v66, v34, v34
	v_fmac_f32_e32 v67, v38, v38
	v_mul_f32_e32 v69, v47, v47
	v_fmac_f32_e32 v68, v42, v42
	v_fmac_f32_e32 v66, v36, v36
	v_fmac_f32_e32 v67, v40, v40
	v_fmac_f32_e32 v69, v46, v46
	v_fmac_f32_e32 v68, v44, v44
	v_fmac_f32_e32 v66, v37, v37
	v_fmac_f32_e32 v67, v41, v41
	v_fmac_f32_e32 v69, v48, v48
	v_fmac_f32_e32 v68, v45, v45
	v_add_f32_e32 v66, v66, v67
	v_fmac_f32_e32 v69, v49, v49
	v_add_f32_e32 v66, v66, v68
	v_add_f32_e32 v73, v66, v69
	v_cvt_pk_bf16_f32 v34, v34, v35
	v_cvt_pk_bf16_f32 v35, v36, v37
	v_cvt_pk_bf16_f32 v36, v38, v39
	v_cvt_pk_bf16_f32 v37, v40, v41
	v_cvt_pk_bf16_f32 v38, v42, v43
	v_cvt_pk_bf16_f32 v39, v44, v45
	v_cvt_pk_bf16_f32 v40, v46, v47
	v_cvt_pk_bf16_f32 v41, v48, v49
	global_store_dwordx2 v188, v[34:35], s[88:89] offset:0
	global_store_dwordx2 v188, v[36:37], s[88:89] offset:512
	global_store_dwordx2 v188, v[38:39], s[88:89] offset:1024
	global_store_dwordx2 v188, v[40:41], s[88:89] offset:1536
	s_lshl_b32 s67, s98, 11
	s_add_u32 s90, s42, s67
	s_addc_u32 s91, s43, 0
	s_waitcnt vmcnt(8)
	v_mul_f32_e32 v66, v51, v51
	v_mul_f32_e32 v67, v55, v55
	v_mul_f32_e32 v68, v59, v59
	v_fmac_f32_e32 v66, v50, v50
	v_fmac_f32_e32 v67, v54, v54
	v_mul_f32_e32 v69, v63, v63
	v_fmac_f32_e32 v68, v58, v58
	v_fmac_f32_e32 v66, v52, v52
	v_fmac_f32_e32 v67, v56, v56
	v_fmac_f32_e32 v69, v62, v62
	v_fmac_f32_e32 v68, v60, v60
	v_fmac_f32_e32 v66, v53, v53
	v_fmac_f32_e32 v67, v57, v57
	v_fmac_f32_e32 v69, v64, v64
	v_fmac_f32_e32 v68, v61, v61
	v_add_f32_e32 v66, v66, v67
	v_fmac_f32_e32 v69, v65, v65
	v_add_f32_e32 v66, v66, v68
	v_add_f32_e32 v74, v66, v69
	v_cvt_pk_bf16_f32 v50, v50, v51
	v_cvt_pk_bf16_f32 v51, v52, v53
	v_cvt_pk_bf16_f32 v52, v54, v55
	v_cvt_pk_bf16_f32 v53, v56, v57
	v_cvt_pk_bf16_f32 v54, v58, v59
	v_cvt_pk_bf16_f32 v55, v60, v61
	v_cvt_pk_bf16_f32 v56, v62, v63
	v_cvt_pk_bf16_f32 v57, v64, v65
	global_store_dwordx2 v188, v[50:51], s[90:91] offset:0
	global_store_dwordx2 v188, v[52:53], s[90:91] offset:512
	global_store_dwordx2 v188, v[54:55], s[90:91] offset:1024
	global_store_dwordx2 v188, v[56:57], s[90:91] offset:1536
	ds_bpermute_b32 v76, v80, v72
	ds_bpermute_b32 v77, v80, v73
	ds_bpermute_b32 v78, v80, v74
	s_waitcnt lgkmcnt(0)
	v_add_f32_e32 v72, v72, v76
	v_add_f32_e32 v73, v73, v77
	v_add_f32_e32 v74, v74, v78
	ds_bpermute_b32 v76, v81, v72
	ds_bpermute_b32 v77, v81, v73
	ds_bpermute_b32 v78, v81, v74
	s_waitcnt lgkmcnt(0)
	v_add_f32_e32 v72, v72, v76
	v_add_f32_e32 v73, v73, v77
	v_add_f32_e32 v74, v74, v78
	ds_bpermute_b32 v76, v82, v72
	ds_bpermute_b32 v77, v82, v73
	ds_bpermute_b32 v78, v82, v74
	s_waitcnt lgkmcnt(0)
	v_add_f32_e32 v72, v72, v76
	v_add_f32_e32 v73, v73, v77
	v_add_f32_e32 v74, v74, v78
	ds_bpermute_b32 v76, v83, v72
	ds_bpermute_b32 v77, v83, v73
	ds_bpermute_b32 v78, v83, v74
	s_waitcnt lgkmcnt(0)
	v_add_f32_e32 v72, v72, v76
	v_add_f32_e32 v73, v73, v77
	v_add_f32_e32 v74, v74, v78
	ds_bpermute_b32 v76, v84, v72
	ds_bpermute_b32 v77, v84, v73
	ds_bpermute_b32 v78, v84, v74
	s_waitcnt lgkmcnt(0)
	v_add_f32_e32 v72, v72, v76
	v_add_f32_e32 v73, v73, v77
	v_add_f32_e32 v74, v74, v78
	ds_bpermute_b32 v76, v85, v72
	ds_bpermute_b32 v77, v85, v73
	ds_bpermute_b32 v78, v85, v74
	s_waitcnt lgkmcnt(0)
	v_add_f32_e32 v72, v72, v76
	v_add_f32_e32 v73, v73, v77
	v_add_f32_e32 v74, v74, v78
	v_fmamk_f32 v72, v72, 0x3a800000, v86
	v_fmamk_f32 v73, v73, 0x3a800000, v86
	v_fmamk_f32 v74, v74, 0x3a800000, v86
	v_rsq_f32_e32 v72, v72
	v_rsq_f32_e32 v73, v73
	v_rsq_f32_e32 v74, v74
	s_nop 0
	s_mov_b64 s[94:95], exec
	s_mov_b64 exec, 1
	s_lshl_b32 s67, s66, 2
	s_add_u32 s92, s42, s67
	s_addc_u32 s93, s43, 0
	s_add_u32 s92, s92, 0x6000000
	s_addc_u32 s93, s93, 0
	global_store_dword v87, v72, s[92:93]
	s_lshl_b32 s67, s97, 2
	s_add_u32 s92, s42, s67
	s_addc_u32 s93, s43, 0
	s_add_u32 s92, s92, 0x6000000
	s_addc_u32 s93, s93, 0
	global_store_dword v87, v73, s[92:93]
	s_lshl_b32 s67, s98, 2
	s_add_u32 s92, s42, s67
	s_addc_u32 s93, s43, 0
	s_add_u32 s92, s92, 0x6000000
	s_addc_u32 s93, s93, 0
	global_store_dword v87, v74, s[92:93]
	s_mov_b64 exec, s[94:95]
	s_waitcnt vmcnt(0)
	s_barrier
	s_cmp_lg_u32 s74, 0
	s_cbranch_scc1 .Lp01_noprod
	s_lshl_b32 s66, s61, 3
	s_add_i32 s66, s66, s96
	s_lshl_b32 s66, s66, 2
	v_mov_b32_e32 v20, s66
	v_mov_b32_e32 v21, 1
	s_add_u32 s68, s42, 0x60d3c20
	s_addc_u32 s69, s43, 0
	s_mov_b64 s[94:95], exec
	s_mov_b64 exec, 1
	global_atomic_add v20, v21, s[68:69] sc1
	s_mov_b64 exec, s[94:95]
.Lp01_noprod:
	s_cmp_lt_u32 s60, 2
	s_cbranch_scc1 .Lp01_nowait
	s_cmp_gt_u32 s60, 7
	s_cbranch_scc1 .Lp01_nowait
	s_cmp_lg_u32 s74, 0
	s_cbranch_scc1 .Lp01_ready
	s_lshl_b32 s66, s61, 3
	s_add_i32 s66, s66, s60
	s_add_i32 s66, s66, -2
	s_lshl_b32 s66, s66, 2
	v_mov_b32_e32 v20, s66
	s_add_u32 s68, s42, 0x60d3c20
	s_addc_u32 s69, s43, 0
	s_mov_b32 s67, 0
.Lp01_spin:
	global_load_dword v21, v20, s[68:69] sc1
	s_waitcnt vmcnt(0)
	v_readfirstlane_b32 s66, v21
	s_cmp_ge_u32 s66, 32
	s_cbranch_scc1 .Lp01_ready
	s_sleep 1
	s_add_i32 s67, s67, 1
	s_cmp_lt_u32 s67, 0x8000
	s_cbranch_scc1 .Lp01_spin

.Lp01_nowait:
	s_lshl_b32 s66, s60, 5
	s_add_i32 s66, s66, s62
	s_mul_i32 s67, s66, 0x2e9
	s_lshr_b32 s67, s67, 13
	s_mul_i32 s68, s67, 11
	s_sub_i32 s68, s66, s68
	s_lshl_b32 s67, s67, 3
	s_add_i32 s67, s67, s61
	s_mul_i32 s33, s67, 11
	s_add_i32 s33, s33, s68
	s_add_i32 s60, s60, 1

.LBB0_320:
	s_mov_b32 s78, 0
	s_waitcnt vmcnt(0)
	s_barrier
	s_mov_b64 s[2:3], exec
	v_readlane_b32 s4, v254, 1
	v_readlane_b32 s5, v254, 2
	s_and_b64 s[4:5], s[2:3], s[4:5]
	s_mov_b64 exec, s[4:5]
	s_cbranch_execz .LBB0_372
	s_add_i32 s4, 0, 0x20000
	v_mov_b32_e32 v0, s4
	s_waitcnt vmcnt(0) expcnt(0) lgkmcnt(0)
	ds_read_b32 v2, v0
	s_add_i32 s4, 0, 0x20004
	v_mov_b32_e32 v0, s4
	ds_read_b32 v0, v0
	s_waitcnt lgkmcnt(1)
	v_cmp_ne_u32_e32 vcc, 0, v2
	s_cbranch_vccnz .LBB0_336
	v_readlane_b32 s4, v254, 0
	s_mul_i32 s11, s69, s4
	s_add_u32 s4, s42, 0x60d0200
	s_addc_u32 s5, s43, 0
	s_add_u32 s6, s42, 0x60d0400
	s_addc_u32 s7, s43, 0
	s_add_u32 s8, s42, 0x60d0500
	s_addc_u32 s9, s43, 0
	s_add_u32 s16, s42, 0x60d0600
	s_addc_u32 s17, s43, 0
	s_add_u32 s18, s42, 0x60d0700
	s_addc_u32 s19, s43, 0
	s_add_u32 s20, s42, 0x60d0800
	s_addc_u32 s21, s43, 0
	s_add_u32 s22, s42, 0x60d0900
	s_addc_u32 s23, s43, 0
	s_add_u32 s24, s42, 0x60d0a00
	s_addc_u32 s25, s43, 0
	s_add_u32 s26, s42, 0x60d0b00
	s_addc_u32 s27, s43, 0
	s_add_u32 s28, s42, 0x60d0c00
	s_addc_u32 s29, s43, 0
	s_add_u32 s30, s42, 0x60d0d00
	s_addc_u32 s31, s43, 0
	s_add_u32 s34, s42, 0x60d0e00
	s_addc_u32 s35, s43, 0
	s_add_u32 s36, s42, 0x60d0f00
	s_addc_u32 s37, s43, 0
	s_add_u32 s44, s42, 0x60d1000
	s_addc_u32 s45, s43, 0
	s_add_u32 s46, s42, 0x60d1100
	s_addc_u32 s47, s43, 0
	s_add_u32 s48, s42, 0x60d1200
	s_addc_u32 s49, s43, 0
	s_add_u32 s50, s42, 0x60d1300
	s_mul_i32 s11, s11, s68
	s_addc_u32 s51, s43, 0
	s_mov_b32 s33, 1
	v_mov_b32_e32 v16, 0
	s_branch .LBB0_324
